# attention lazy rescale v2: per-half-wave tile max tested against m+8 first; cross-half exchange and exact max only on the (rare) rescale path
# speedup vs baseline: 1.0560x; 1.0069x over previous
; template <int DV, int MODE>
; DI void attn_item(const AttnArgs& a, char* smem) {
;     ...
;     __syncthreads();
;     *(u32x4*)(Ks1 + srow * 72 + sch * 8) = rk1;
;     if (MODE == 1) *(u32x4*)(Ks2 + srow * 72 + sch * 8) = rk2;
; #pragma unroll
;     for (int j = 0; j < NVL; ++j) *(u32x4*)(Vs + (srow + 64 * j) * 72 + sch * 8) = rv[j];
;     __syncthreads();
;     if (tt + 1 < nt) ATTN_FETCH(tt + 1)
;     ...
;       f32x16 s[2];
; #pragma unroll
;       for (int kb = 0; kb < 2; ++kb) {
; #pragma unroll
;         for (int i = 0; i < 16; ++i) s[kb][i] = 0.f;
; #pragma unroll
;         for (int ks = 0; ks < 4; ++ks) {
;           const bf8 kf = *(const bf8*)(Ks + (kb * 32 + r) * 72 + ks * 16 + h * 8);
;           s[kb] = mfma32(kf, qf[ks], s[kb]);
;         }
;       }
;       constexpr float SC = 0.125f * LOG2E;
;       float mx = -INFINITY;
;       if (local) {
; #pragma unroll
;         for (int kb = 0; kb < 2; ++kb)
; #pragma unroll
;           for (int i = 0; i < 16; ++i) {
;             const int kc = kb * 32 + crow(i, h);
;             const bool ok = (kc >= cs) && (kc < cs + 16);
;             const int dc = kc - qc + 15;
;             const int dr = kr - rq + 7;
;             const float bias = rpbS[dr * 32 + (ok ? dc : 0)];
;             const float v = ok ? (s[kb][i] + bias * (1.f / SC)) : -INFINITY;
;             s[kb][i] = v;
;             mx = fmaxf(mx, v);
;           }
;       } else {
; #pragma unroll
;         for (int kb = 0; kb < 2; ++kb)
; #pragma unroll
;           for (int i = 0; i < 16; i += 2) mx = fmaxf(fmaxf(mx, s[kb][i]), s[kb][i + 1]);
;       }
;       mx = fmaxf(mx, shx(mx, lane, 32)) * SC;
;       const float mn = fmaxf(m, mx);
;       const bool resc = __builtin_amdgcn_ballot_w64(mn != m) != 0ull;
;       float ps0 = 0.f, ps1 = 0.f;
; #pragma unroll
;       for (int kb = 0; kb < 2; ++kb)
; #pragma unroll
;         for (int i = 0; i < 16; i += 2) {
;           f32x2n v = {s[kb][i], s[kb][i + 1]};
;           v = v * f32x2n{SC, SC} - f32x2n{mn, mn};
;           const float p0 = ex2(v.x), p1 = ex2(v.y);
;           s[kb][i] = p0; s[kb][i + 1] = p1;
;           ps0 += p0; ps1 += p1;
;         }
;       if (resc) {
;         const float alpha = ex2(m - mn);
;         m = mn;
;         lsum *= alpha;
; #pragma unroll
;         for (int d = 0; d < NDV; ++d)
; #pragma unroll
;           for (int i = 0; i < 16; ++i) O[d][i] *= alpha;
;       }
.LBB0_415:
	v_lshl_add_u64 v[34:35], v[98:99], 0, s[2:3]
	s_barrier
	s_waitcnt vmcnt(1)
	ds_write_b128 v94, v[82:85]
	s_waitcnt vmcnt(0)
	ds_write_b128 v94, v[86:89] offset:18432
	s_waitcnt lgkmcnt(0)
	s_barrier
	global_load_dwordx4 v[82:85], v[96:97], off
	global_load_dwordx4 v[86:89], v[34:35], off
	v_add_u32_e32 v103, v92, v102
	ds_read_b128 v[34:37], v103
	ds_read_b128 v[38:41], v103 offset:32
	ds_read_b128 v[106:109], v103 offset:4640
	s_waitcnt lgkmcnt(2)
	v_mfma_f32_32x32x16_bf16 v[50:65], v[34:37], v[78:81], 0
	ds_read_b128 v[34:37], v103 offset:64
	s_waitcnt lgkmcnt(2)
	v_mfma_f32_32x32x16_bf16 v[50:65], v[38:41], v[74:77], v[50:65]
	s_waitcnt lgkmcnt(0)
	v_mfma_f32_32x32x16_bf16 v[50:65], v[34:37], v[70:73], v[50:65]
	ds_read_b128 v[34:37], v103 offset:96
	s_waitcnt lgkmcnt(0)
	v_mfma_f32_32x32x16_bf16 v[50:65], v[34:37], v[66:69], v[50:65]
	ds_read_b128 v[34:37], v103 offset:4608
	s_waitcnt lgkmcnt(0)
	v_mfma_f32_32x32x16_bf16 v[34:49], v[34:37], v[78:81], 0
	s_nop 8
	v_max3_f32 v100, v50, s33, v51
	v_max3_f32 v100, v100, v52, v53
	v_max3_f32 v100, v100, v54, v55
	v_max3_f32 v100, v100, v56, v57
	v_max3_f32 v100, v100, v58, v59
	v_max3_f32 v100, v100, v60, v61
	v_max3_f32 v100, v100, v62, v63
	v_mfma_f32_32x32x16_bf16 v[34:49], v[106:109], v[74:77], v[34:49]
	ds_read_b128 v[106:109], v103 offset:4672
	v_max3_f32 v100, v100, v64, v65
	s_waitcnt lgkmcnt(0)
	v_mfma_f32_32x32x16_bf16 v[34:49], v[106:109], v[70:73], v[34:49]
	ds_read_b128 v[106:109], v103 offset:4704
	s_waitcnt lgkmcnt(0)
	v_mfma_f32_32x32x16_bf16 v[34:49], v[106:109], v[66:69], v[34:49]
	s_nop 11
	v_max3_f32 v100, v100, v34, v35
	v_max3_f32 v100, v100, v36, v37
	v_max3_f32 v100, v100, v38, v39
	v_max3_f32 v100, v100, v40, v41
	v_max3_f32 v100, v100, v42, v43
	v_max3_f32 v100, v100, v44, v45
	v_max3_f32 v100, v100, v46, v47
	v_max3_f32 v100, v100, v48, v49
	v_mul_f32_e32 v101, 0x3e38aa3b, v100
	v_sub_f32_e32 v101, v101, v105
	v_cmp_lt_f32_e32 vcc, 8.0, v101
	s_cbranch_vccnz .Llz_0
	v_mov_b32_e32 v100, v105
	s_branch .LBB0_414
.Llz_0:
	ds_bpermute_b32 v101, v93, v100
	s_waitcnt lgkmcnt(0)
	v_max_f32_e32 v101, v101, v101
	v_max_f32_e32 v100, v100, v101
	v_mul_f32_e32 v100, 0x3e38aa3b, v100
	v_max_f32_e32 v101, v105, v105
	v_max_f32_e32 v100, v101, v100
	v_cmp_neq_f32_e32 vcc, v100, v105
	s_cbranch_vccz .LBB0_414
	v_sub_f32_e32 v101, v105, v100
	v_exp_f32_e32 v106, v101
	v_mov_b32_e32 v105, v100
	v_pk_mul_f32 v[32:33], v[32:33], v[106:107] op_sel_hi:[1,0]
	v_pk_mul_f32 v[30:31], v[30:31], v[106:107] op_sel_hi:[1,0]
	v_pk_mul_f32 v[28:29], v[28:29], v[106:107] op_sel_hi:[1,0]
	v_pk_mul_f32 v[26:27], v[26:27], v[106:107] op_sel_hi:[1,0]
	v_pk_mul_f32 v[24:25], v[24:25], v[106:107] op_sel_hi:[1,0]
	v_pk_mul_f32 v[22:23], v[22:23], v[106:107] op_sel_hi:[1,0]
	v_pk_mul_f32 v[20:21], v[20:21], v[106:107] op_sel_hi:[1,0]
	v_pk_mul_f32 v[18:19], v[18:19], v[106:107] op_sel_hi:[1,0]
	v_pk_mul_f32 v[16:17], v[16:17], v[106:107] op_sel_hi:[1,0]
	v_pk_mul_f32 v[14:15], v[14:15], v[106:107] op_sel_hi:[1,0]
	v_pk_mul_f32 v[12:13], v[12:13], v[106:107] op_sel_hi:[1,0]
	v_pk_mul_f32 v[10:11], v[10:11], v[106:107] op_sel_hi:[1,0]
	v_pk_mul_f32 v[8:9], v[8:9], v[106:107] op_sel_hi:[1,0]
	v_pk_mul_f32 v[6:7], v[6:7], v[106:107] op_sel_hi:[1,0]
	v_pk_mul_f32 v[4:5], v[4:5], v[106:107] op_sel_hi:[1,0]
	v_pk_mul_f32 v[2:3], v[2:3], v[106:107] op_sel_hi:[1,0]
	v_mul_f32_e32 v95, v95, v106
	s_branch .LBB0_414
.LBB0_417:
	s_barrier
	s_waitcnt vmcnt(1)
	ds_write_b128 v94, v[82:85]
	s_waitcnt vmcnt(0)
	ds_write_b128 v94, v[86:89] offset:18432
	s_waitcnt lgkmcnt(0)
	s_barrier
	ds_read_b128 v[34:37], v103
	ds_read_b128 v[38:41], v103 offset:32
	s_waitcnt lgkmcnt(1)
	v_mfma_f32_32x32x16_bf16 v[50:65], v[34:37], v[78:81], 0
	ds_read_b128 v[34:37], v103 offset:64
	s_waitcnt lgkmcnt(1)
	v_mfma_f32_32x32x16_bf16 v[50:65], v[38:41], v[74:77], v[50:65]
	s_waitcnt lgkmcnt(0)
	v_mfma_f32_32x32x16_bf16 v[50:65], v[34:37], v[70:73], v[50:65]
	ds_read_b128 v[34:37], v103 offset:96
	s_waitcnt lgkmcnt(0)
	v_mfma_f32_32x32x16_bf16 v[50:65], v[34:37], v[66:69], v[50:65]
	ds_read_b128 v[34:37], v103 offset:4608
	s_waitcnt lgkmcnt(0)
	v_mfma_f32_32x32x16_bf16 v[34:49], v[34:37], v[78:81], 0
	ds_read_b128 v[78:81], v103 offset:4640
	s_waitcnt lgkmcnt(0)
	v_mfma_f32_32x32x16_bf16 v[34:49], v[78:81], v[74:77], v[34:49]
	ds_read_b128 v[74:77], v103 offset:4672
	s_waitcnt lgkmcnt(0)
	v_mfma_f32_32x32x16_bf16 v[34:49], v[74:77], v[70:73], v[34:49]
	ds_read_b128 v[70:73], v103 offset:4704
	s_waitcnt lgkmcnt(0)
	v_mfma_f32_32x32x16_bf16 v[34:49], v[70:73], v[66:69], v[34:49]
	v_max3_f32 v66, v50, s33, v51
	v_max3_f32 v66, v66, v52, v53
	v_max3_f32 v66, v66, v54, v55
	v_max3_f32 v66, v66, v56, v57
	v_max3_f32 v66, v66, v58, v59
	v_max3_f32 v66, v66, v60, v61
	v_max3_f32 v66, v66, v62, v63
	v_max3_f32 v66, v66, v64, v65
	s_nop 3
	v_max3_f32 v66, v66, v34, v35
	v_max3_f32 v66, v66, v36, v37
	v_max3_f32 v66, v66, v38, v39
	v_max3_f32 v66, v66, v40, v41
	v_max3_f32 v66, v66, v42, v43
	v_max3_f32 v66, v66, v44, v45
	v_max3_f32 v66, v66, v46, v47
	v_max3_f32 v66, v66, v48, v49
	v_mul_f32_e32 v67, 0x3e38aa3b, v66
	v_sub_f32_e32 v67, v67, v105
	v_cmp_lt_f32_e32 vcc, 8.0, v67
	s_cbranch_vccnz .Llz_1
	v_mov_b32_e32 v66, v105
	s_branch .LBB0_419
.Llz_1:
	ds_bpermute_b32 v67, v93, v66
	s_waitcnt lgkmcnt(0)
	v_max_f32_e32 v67, v67, v67
	v_max_f32_e32 v66, v66, v67
	v_mul_f32_e32 v66, 0x3e38aa3b, v66
	v_max_f32_e32 v67, v105, v105
	v_max_f32_e32 v66, v67, v66
	v_cmp_neq_f32_e32 vcc, v66, v105
	s_cbranch_vccz .LBB0_419
	v_sub_f32_e32 v67, v105, v66
	v_exp_f32_e32 v68, v67
	s_nop 0
	v_pk_mul_f32 v[32:33], v[32:33], v[68:69] op_sel_hi:[1,0]
	v_pk_mul_f32 v[30:31], v[30:31], v[68:69] op_sel_hi:[1,0]
	v_pk_mul_f32 v[28:29], v[28:29], v[68:69] op_sel_hi:[1,0]
	v_pk_mul_f32 v[26:27], v[26:27], v[68:69] op_sel_hi:[1,0]
	v_pk_mul_f32 v[24:25], v[24:25], v[68:69] op_sel_hi:[1,0]
	v_pk_mul_f32 v[22:23], v[22:23], v[68:69] op_sel_hi:[1,0]
	v_pk_mul_f32 v[20:21], v[20:21], v[68:69] op_sel_hi:[1,0]
	v_pk_mul_f32 v[18:19], v[18:19], v[68:69] op_sel_hi:[1,0]
	v_pk_mul_f32 v[16:17], v[16:17], v[68:69] op_sel_hi:[1,0]
	v_pk_mul_f32 v[14:15], v[14:15], v[68:69] op_sel_hi:[1,0]
	v_pk_mul_f32 v[12:13], v[12:13], v[68:69] op_sel_hi:[1,0]
	v_pk_mul_f32 v[10:11], v[10:11], v[68:69] op_sel_hi:[1,0]
	v_pk_mul_f32 v[8:9], v[8:9], v[68:69] op_sel_hi:[1,0]
	v_pk_mul_f32 v[6:7], v[6:7], v[68:69] op_sel_hi:[1,0]
	v_pk_mul_f32 v[4:5], v[4:5], v[68:69] op_sel_hi:[1,0]
	v_pk_mul_f32 v[2:3], v[2:3], v[68:69] op_sel_hi:[1,0]
	v_mul_f32_e32 v95, v95, v68

; DI f32x16 mfma32(bf8 a, bf8 b, f32x16 c) { return __builtin_amdgcn_mfma_f32_32x32x16_bf16(a, b, c, 0, 0, 0); }
; DI float ex2(float x) { return __builtin_amdgcn_exp2f(x); }
; DI float shx(float v, int lane, int mask) { return __int_as_float(__builtin_amdgcn_ds_bpermute((lane ^ mask) << 2, __float_as_int(v))); }
; DI void attn_item_q64(const AttnArgs& a, char* smem) {
;     ...
;   for (int tt = 0; tt < nt; ++tt) {
;     const char* Ks = Kb_ + (tt & 1) * 8192;
;     const char* Vs = Vb_ + (tt & 1) * 8192;
;     f32x16 s[2][2];
; #pragma unroll
;     for (int kb = 0; kb < 2; ++kb) {
; #pragma unroll
;       for (int q2 = 0; q2 < 2; ++q2)
; #pragma unroll
;         for (int i = 0; i < 16; ++i) s[q2][kb][i] = 0.f;
; #pragma unroll
;       for (int ks = 0; ks < 4; ++ks) {
;         const bf8 kf = *(const bf8*)(Ks + kb * 32 * 128 + koff[ks]);
; #pragma unroll
;         for (int q2 = 0; q2 < 2; ++q2) s[q2][kb] = mfma32(kf, qf[q2][ks], s[q2][kb]);
;       }
;     }
;     constexpr float SC = 0.125f * LOG2E;
; #pragma unroll
;     for (int q2 = 0; q2 < 2; ++q2) {
;       float mx = -INFINITY;
; #pragma unroll
;       for (int kb = 0; kb < 2; ++kb)
; #pragma unroll
;         for (int i = 0; i < 16; i += 2) mx = fmaxf(fmaxf(mx, s[q2][kb][i]), s[q2][kb][i + 1]);
;       mx = fmaxf(mx, shx(mx, lane, 32)) * SC;
;       const float mn = fmaxf(m[q2], mx);
;       const bool resc = __builtin_amdgcn_ballot_w64(mn != m[q2]) != 0ull;
;       float ps0 = 0.f, ps1 = 0.f;
; #pragma unroll
;       for (int kb = 0; kb < 2; ++kb)
; #pragma unroll
;         for (int i = 0; i < 16; i += 2) {
;           f32x2n v = {s[q2][kb][i], s[q2][kb][i + 1]};
;           v = v * f32x2n{SC, SC} - f32x2n{mn, mn};
;           const float p0 = ex2(v.x), p1 = ex2(v.y);
;           s[q2][kb][i] = p0; s[q2][kb][i + 1] = p1;
;           ps0 += p0; ps1 += p1;
;         }
;       if (resc) {
;         const float alpha = ex2(m[q2] - mn);
;         m[q2] = mn;
;         lsum[q2] *= alpha;
; #pragma unroll
;         for (int d = 0; d < 2; ++d)
; #pragma unroll
;           for (int i = 0; i < 16; ++i) O[q2][d][i] *= alpha;
;       }
.LBB0_423:
	s_and_b32 s14, s2, 0x2000
	v_or_b32_e32 v0, s14, v176
	s_waitcnt vmcnt(19)
	ds_read_b128 v[66:69], v0
	v_or_b32_e32 v172, s14, v177
	s_waitcnt vmcnt(17)
	ds_read_b128 v[82:85], v172
	v_or_b32_e32 v196, s14, v178
	v_or_b32_e32 v197, s14, v179
	ds_read_b128 v[192:195], v172 offset:4096
	s_waitcnt vmcnt(7) lgkmcnt(2)
	v_mfma_f32_32x32x16_bf16 v[98:113], v[66:69], v[130:133], 0
	s_waitcnt vmcnt(3)
	v_mfma_f32_32x32x16_bf16 v[66:81], v[66:69], v[146:149], 0
	s_waitcnt lgkmcnt(1)
	v_mfma_f32_32x32x16_bf16 v[98:113], v[82:85], v[134:137], v[98:113]
	s_waitcnt vmcnt(2)
	v_mfma_f32_32x32x16_bf16 v[66:81], v[82:85], v[150:153], v[66:81]
	ds_read_b128 v[82:85], v196
	s_waitcnt lgkmcnt(0)
	v_mfma_f32_32x32x16_bf16 v[98:113], v[82:85], v[138:141], v[98:113]
	s_waitcnt vmcnt(1)
	v_mfma_f32_32x32x16_bf16 v[66:81], v[82:85], v[154:157], v[66:81]
	ds_read_b128 v[82:85], v197
	s_waitcnt lgkmcnt(0)
	v_mfma_f32_32x32x16_bf16 v[98:113], v[82:85], v[142:145], v[98:113]
	s_waitcnt vmcnt(0)
	v_mfma_f32_32x32x16_bf16 v[66:81], v[82:85], v[158:161], v[66:81]
	ds_read_b128 v[82:85], v0 offset:4096
	s_nop 8
	v_max3_f32 v0, v98, s33, v99
	v_max3_f32 v0, v0, v100, v101
	v_max3_f32 v0, v0, v102, v103
	v_max3_f32 v0, v0, v104, v105
	v_max3_f32 v0, v0, v106, v107
	v_max3_f32 v0, v0, v108, v109
	s_waitcnt lgkmcnt(0)
	v_mfma_f32_32x32x16_bf16 v[114:129], v[82:85], v[130:133], 0
	v_max3_f32 v0, v0, v110, v111
	v_max3_f32 v0, v0, v112, v113
	v_mfma_f32_32x32x16_bf16 v[82:97], v[82:85], v[146:149], 0
	v_mfma_f32_32x32x16_bf16 v[114:129], v[192:195], v[134:137], v[114:129]
	v_mfma_f32_32x32x16_bf16 v[82:97], v[192:195], v[150:153], v[82:97]
	ds_read_b128 v[192:195], v196 offset:4096
	s_waitcnt lgkmcnt(0)
	v_mfma_f32_32x32x16_bf16 v[114:129], v[192:195], v[138:141], v[114:129]
	v_mfma_f32_32x32x16_bf16 v[82:97], v[192:195], v[154:157], v[82:97]
	ds_read_b128 v[192:195], v197 offset:4096
	s_waitcnt lgkmcnt(0)
	v_mfma_f32_32x32x16_bf16 v[114:129], v[192:195], v[142:145], v[114:129]
	v_mfma_f32_32x32x16_bf16 v[82:97], v[192:195], v[158:161], v[82:97]
	s_nop 10
	v_max3_f32 v0, v0, v114, v115
	v_max3_f32 v0, v0, v116, v117
	v_max3_f32 v0, v0, v118, v119
	v_max3_f32 v0, v0, v120, v121
	v_max3_f32 v0, v0, v122, v123
	v_max3_f32 v0, v0, v124, v125
	v_max3_f32 v0, v0, v126, v127
	v_max3_f32 v0, v0, v128, v129
	v_mul_f32_e32 v172, 0x3e38aa3b, v0
	v_sub_f32_e32 v172, v172, v191
	v_cmp_lt_f32_e32 vcc, 8.0, v172
	s_cbranch_vccnz .Llz_2
	v_mov_b32_e32 v0, v191
	s_branch .LBB0_425
.Llz_2:
	ds_bpermute_b32 v172, v173, v0
	s_waitcnt lgkmcnt(0)
	v_max_f32_e32 v172, v172, v172
	v_max_f32_e32 v0, v0, v172
	v_mul_f32_e32 v0, 0x3e38aa3b, v0
	v_max_f32_e32 v172, v191, v191
	v_max_f32_e32 v0, v172, v0
	v_cmp_neq_f32_e32 vcc, v0, v191
	s_cbranch_vccz .LBB0_425
	v_sub_f32_e32 v172, v191, v0
	v_exp_f32_e32 v172, v172
	v_mov_b32_e32 v191, v0
	v_mul_f32_e32 v189, v189, v172
	v_pk_mul_f32 v[64:65], v[64:65], v[172:173] op_sel_hi:[1,0]
	v_pk_mul_f32 v[62:63], v[62:63], v[172:173] op_sel_hi:[1,0]
	v_pk_mul_f32 v[60:61], v[60:61], v[172:173] op_sel_hi:[1,0]
	v_pk_mul_f32 v[58:59], v[58:59], v[172:173] op_sel_hi:[1,0]
	v_pk_mul_f32 v[56:57], v[56:57], v[172:173] op_sel_hi:[1,0]
	v_pk_mul_f32 v[54:55], v[54:55], v[172:173] op_sel_hi:[1,0]
	v_pk_mul_f32 v[52:53], v[52:53], v[172:173] op_sel_hi:[1,0]
	v_pk_mul_f32 v[50:51], v[50:51], v[172:173] op_sel_hi:[1,0]
	v_pk_mul_f32 v[48:49], v[48:49], v[172:173] op_sel_hi:[1,0]
	v_pk_mul_f32 v[46:47], v[46:47], v[172:173] op_sel_hi:[1,0]
	v_pk_mul_f32 v[44:45], v[44:45], v[172:173] op_sel_hi:[1,0]
	v_pk_mul_f32 v[42:43], v[42:43], v[172:173] op_sel_hi:[1,0]
	v_pk_mul_f32 v[40:41], v[40:41], v[172:173] op_sel_hi:[1,0]
	v_pk_mul_f32 v[38:39], v[38:39], v[172:173] op_sel_hi:[1,0]
	v_pk_mul_f32 v[36:37], v[36:37], v[172:173] op_sel_hi:[1,0]
	v_pk_mul_f32 v[34:35], v[34:35], v[172:173] op_sel_hi:[1,0]
.LBB0_425:
	v_max3_f32 v172, v66, s33, v67
	v_max3_f32 v172, v172, v68, v69
	v_max3_f32 v172, v172, v70, v71
	v_max3_f32 v172, v172, v72, v73
	v_max3_f32 v172, v172, v74, v75
	v_max3_f32 v172, v172, v76, v77
	v_max3_f32 v172, v172, v78, v79
	v_max3_f32 v172, v172, v80, v81
	v_max3_f32 v172, v172, v82, v83
	v_max3_f32 v172, v172, v84, v85
	v_max3_f32 v172, v172, v86, v87
	v_max3_f32 v172, v172, v88, v89
	v_max3_f32 v172, v172, v90, v91
	v_max3_f32 v172, v172, v92, v93
	v_max3_f32 v172, v172, v94, v95
	v_max3_f32 v172, v172, v96, v97
	v_mul_f32_e32 v192, 0x3e38aa3b, v172
	v_sub_f32_e32 v192, v192, v190
	v_cmp_lt_f32_e32 vcc, 8.0, v192
	s_cbranch_vccnz .Llz_3
	s_waitcnt lgkmcnt(0)
	v_mov_b32_e32 v172, v190
	s_branch .LBB0_427
.Llz_3:
	ds_bpermute_b32 v192, v173, v172
	s_waitcnt lgkmcnt(0)
	v_max_f32_e32 v192, v192, v192
	v_max_f32_e32 v172, v172, v192
	v_mul_f32_e32 v172, 0x3e38aa3b, v172
	v_max_f32_e32 v192, v190, v190
	v_max_f32_e32 v172, v192, v172
	v_cmp_neq_f32_e32 vcc, v172, v190
	s_cbranch_vccz .LBB0_427
	v_sub_f32_e32 v190, v190, v172
	v_exp_f32_e32 v190, v190
	s_nop 0
	v_mul_f32_e32 v174, v174, v190
	v_pk_mul_f32 v[32:33], v[32:33], v[190:191] op_sel_hi:[1,0]
	v_pk_mul_f32 v[30:31], v[30:31], v[190:191] op_sel_hi:[1,0]
	v_pk_mul_f32 v[28:29], v[28:29], v[190:191] op_sel_hi:[1,0]
	v_pk_mul_f32 v[26:27], v[26:27], v[190:191] op_sel_hi:[1,0]
	v_pk_mul_f32 v[24:25], v[24:25], v[190:191] op_sel_hi:[1,0]
	v_pk_mul_f32 v[22:23], v[22:23], v[190:191] op_sel_hi:[1,0]
	v_pk_mul_f32 v[20:21], v[20:21], v[190:191] op_sel_hi:[1,0]
	v_pk_mul_f32 v[18:19], v[18:19], v[190:191] op_sel_hi:[1,0]
	v_pk_mul_f32 v[16:17], v[16:17], v[190:191] op_sel_hi:[1,0]
	v_pk_mul_f32 v[14:15], v[14:15], v[190:191] op_sel_hi:[1,0]
	v_pk_mul_f32 v[12:13], v[12:13], v[190:191] op_sel_hi:[1,0]
	v_pk_mul_f32 v[10:11], v[10:11], v[190:191] op_sel_hi:[1,0]
	v_pk_mul_f32 v[8:9], v[8:9], v[190:191] op_sel_hi:[1,0]
	v_pk_mul_f32 v[6:7], v[6:7], v[190:191] op_sel_hi:[1,0]
	v_pk_mul_f32 v[4:5], v[4:5], v[190:191] op_sel_hi:[1,0]
	v_pk_mul_f32 v[2:3], v[2:3], v[190:191] op_sel_hi:[1,0]
	v_mov_b32_e32 v190, v172

; DI int crow(int i, int h) { return (i & 3) + 8 * (i >> 2) + 4 * h; }
; DI f32x16 mfma32(bf8 a, bf8 b, f32x16 c) { return __builtin_amdgcn_mfma_f32_32x32x16_bf16(a, b, c, 0, 0, 0); }
; DI float ex2(float x) { return __builtin_amdgcn_exp2f(x); }
; template <int DV, int MODE>
; DI void attn_item(const AttnArgs& a, char* smem) {
;     ...
;       f32x16 s[2];
; #pragma unroll
;       for (int kb = 0; kb < 2; ++kb) {
; #pragma unroll
;         for (int i = 0; i < 16; ++i) s[kb][i] = 0.f;
; #pragma unroll
;         for (int ks = 0; ks < 4; ++ks) {
;           const bf8 kf = *(const bf8*)(Ks + (kb * 32 + r) * 72 + ks * 16 + h * 8);
;           s[kb] = mfma32(kf, qf[ks], s[kb]);
;         }
;       }
;       constexpr float SC = 0.125f * LOG2E;
;       float mx = -INFINITY;
;       if (local) {
; #pragma unroll
;         for (int kb = 0; kb < 2; ++kb)
; #pragma unroll
;           for (int i = 0; i < 16; ++i) {
;             const int kc = kb * 32 + crow(i, h);
;             const bool ok = (kc >= cs) && (kc < cs + 16);
;             const int dc = kc - qc + 15;
;             const int dr = kr - rq + 7;
;             const float bias = rpbS[dr * 32 + (ok ? dc : 0)];
;             const float v = ok ? (s[kb][i] + bias * (1.f / SC)) : -INFINITY;
;             s[kb][i] = v;
;             mx = fmaxf(mx, v);
;           }
;       } else {
; #pragma unroll
;         for (int kb = 0; kb < 2; ++kb)
; #pragma unroll
;           for (int i = 0; i < 16; i += 2) mx = fmaxf(fmaxf(mx, s[kb][i]), s[kb][i + 1]);
;       }
;       mx = fmaxf(mx, shx(mx, lane, 32)) * SC;
;       const float mn = fmaxf(m, mx);
;       const bool resc = __builtin_amdgcn_ballot_w64(mn != m) != 0ull;
;       float ps0 = 0.f, ps1 = 0.f;
; #pragma unroll
;       for (int kb = 0; kb < 2; ++kb)
; #pragma unroll
;         for (int i = 0; i < 16; i += 2) {
;           f32x2n v = {s[kb][i], s[kb][i + 1]};
;           v = v * f32x2n{SC, SC} - f32x2n{mn, mn};
;           const float p0 = ex2(v.x), p1 = ex2(v.y);
;           s[kb][i] = p0; s[kb][i + 1] = p1;
;           ps0 += p0; ps1 += p1;
;         }
;       if (resc) {
;         const float alpha = ex2(m - mn);
;         m = mn;
;         lsum *= alpha;
; #pragma unroll
;         for (int d = 0; d < NDV; ++d)
; #pragma unroll
;           for (int i = 0; i < 16; ++i) O[d][i] *= alpha;
;       }
.LBB0_441:
	ds_read_b128 v[66:69], v146
	ds_read_b128 v[70:73], v146 offset:32
	ds_read_b128 v[150:153], v146 offset:4640
	s_waitcnt lgkmcnt(2)
	v_mfma_f32_32x32x16_bf16 v[82:97], v[66:69], v[98:101], 0
	ds_read_b128 v[66:69], v146 offset:64
	s_waitcnt lgkmcnt(2)
	v_mfma_f32_32x32x16_bf16 v[82:97], v[70:73], v[102:105], v[82:97]
	s_waitcnt lgkmcnt(0)
	v_mfma_f32_32x32x16_bf16 v[82:97], v[66:69], v[106:109], v[82:97]
	ds_read_b128 v[66:69], v146 offset:96
	s_waitcnt lgkmcnt(0)
	v_mfma_f32_32x32x16_bf16 v[82:97], v[66:69], v[110:113], v[82:97]
	ds_read_b128 v[66:69], v146 offset:4608
	s_waitcnt lgkmcnt(0)
	v_mfma_f32_32x32x16_bf16 v[66:81], v[66:69], v[98:101], 0
	s_nop 8
	v_max3_f32 v142, v82, s33, v83
	v_max3_f32 v142, v142, v84, v85
	v_max3_f32 v142, v142, v86, v87
	v_max3_f32 v142, v142, v88, v89
	v_max3_f32 v142, v142, v90, v91
	v_max3_f32 v142, v142, v92, v93
	v_max3_f32 v142, v142, v94, v95
	v_mfma_f32_32x32x16_bf16 v[66:81], v[150:153], v[102:105], v[66:81]
	ds_read_b128 v[150:153], v146 offset:4672
	v_max3_f32 v142, v142, v96, v97
	s_waitcnt lgkmcnt(0)
	v_mfma_f32_32x32x16_bf16 v[66:81], v[150:153], v[106:109], v[66:81]
	ds_read_b128 v[150:153], v146 offset:4704
	s_waitcnt lgkmcnt(0)
	v_mfma_f32_32x32x16_bf16 v[66:81], v[150:153], v[110:113], v[66:81]
	s_nop 11
	v_max3_f32 v142, v142, v66, v67
	v_max3_f32 v142, v142, v68, v69
	v_max3_f32 v142, v142, v70, v71
	v_max3_f32 v142, v142, v72, v73
	v_max3_f32 v142, v142, v74, v75
	v_max3_f32 v142, v142, v76, v77
	v_max3_f32 v142, v142, v78, v79
	v_max3_f32 v142, v142, v80, v81
	v_mul_f32_e32 v150, 0x3e38aa3b, v142
	v_sub_f32_e32 v150, v150, v148
	v_cmp_lt_f32_e32 vcc, 8.0, v150
	s_cbranch_vccnz .Llz_4
	v_mov_b32_e32 v142, v148
	s_branch .LBB0_438
.Llz_4:
	ds_bpermute_b32 v150, v133, v142
	s_waitcnt lgkmcnt(0)
	v_max_f32_e32 v150, v150, v150
	v_max_f32_e32 v142, v142, v150
	v_mul_f32_e32 v142, 0x3e38aa3b, v142
	v_max_f32_e32 v150, v148, v148
	v_max_f32_e32 v142, v150, v142
	v_cmp_neq_f32_e32 vcc, v142, v148
	s_cbranch_vccz .LBB0_438
	v_sub_f32_e32 v148, v148, v142
	v_exp_f32_e32 v148, v148
	s_nop 0
	v_pk_mul_f32 v[64:65], v[64:65], v[148:149] op_sel_hi:[1,0]
	v_pk_mul_f32 v[62:63], v[62:63], v[148:149] op_sel_hi:[1,0]
	v_pk_mul_f32 v[60:61], v[60:61], v[148:149] op_sel_hi:[1,0]
	v_pk_mul_f32 v[58:59], v[58:59], v[148:149] op_sel_hi:[1,0]
	v_pk_mul_f32 v[56:57], v[56:57], v[148:149] op_sel_hi:[1,0]
	v_pk_mul_f32 v[54:55], v[54:55], v[148:149] op_sel_hi:[1,0]
	v_pk_mul_f32 v[52:53], v[52:53], v[148:149] op_sel_hi:[1,0]
	v_pk_mul_f32 v[50:51], v[50:51], v[148:149] op_sel_hi:[1,0]
	v_pk_mul_f32 v[48:49], v[48:49], v[148:149] op_sel_hi:[1,0]
	v_pk_mul_f32 v[46:47], v[46:47], v[148:149] op_sel_hi:[1,0]
	v_pk_mul_f32 v[44:45], v[44:45], v[148:149] op_sel_hi:[1,0]
	v_pk_mul_f32 v[42:43], v[42:43], v[148:149] op_sel_hi:[1,0]
	v_pk_mul_f32 v[40:41], v[40:41], v[148:149] op_sel_hi:[1,0]
	v_pk_mul_f32 v[38:39], v[38:39], v[148:149] op_sel_hi:[1,0]
	v_pk_mul_f32 v[36:37], v[36:37], v[148:149] op_sel_hi:[1,0]
	v_pk_mul_f32 v[34:35], v[34:35], v[148:149] op_sel_hi:[1,0]
	v_pk_mul_f32 v[32:33], v[32:33], v[148:149] op_sel_hi:[1,0]
	v_pk_mul_f32 v[30:31], v[30:31], v[148:149] op_sel_hi:[1,0]
	v_pk_mul_f32 v[28:29], v[28:29], v[148:149] op_sel_hi:[1,0]
	v_pk_mul_f32 v[26:27], v[26:27], v[148:149] op_sel_hi:[1,0]
	v_pk_mul_f32 v[24:25], v[24:25], v[148:149] op_sel_hi:[1,0]
	v_pk_mul_f32 v[22:23], v[22:23], v[148:149] op_sel_hi:[1,0]
	v_pk_mul_f32 v[20:21], v[20:21], v[148:149] op_sel_hi:[1,0]
	v_pk_mul_f32 v[18:19], v[18:19], v[148:149] op_sel_hi:[1,0]
	v_pk_mul_f32 v[16:17], v[16:17], v[148:149] op_sel_hi:[1,0]
	v_pk_mul_f32 v[14:15], v[14:15], v[148:149] op_sel_hi:[1,0]
	v_pk_mul_f32 v[12:13], v[12:13], v[148:149] op_sel_hi:[1,0]
	v_pk_mul_f32 v[10:11], v[10:11], v[148:149] op_sel_hi:[1,0]
	v_pk_mul_f32 v[8:9], v[8:9], v[148:149] op_sel_hi:[1,0]
	v_pk_mul_f32 v[6:7], v[6:7], v[148:149] op_sel_hi:[1,0]
	v_pk_mul_f32 v[4:5], v[4:5], v[148:149] op_sel_hi:[1,0]
	v_pk_mul_f32 v[2:3], v[2:3], v[148:149] op_sel_hi:[1,0]
	v_mul_f32_e32 v145, v145, v148
	v_mov_b32_e32 v148, v142
	s_branch .LBB0_438

; DI float ex2(float x) { return __builtin_amdgcn_exp2f(x); }
; DI float shx(float v, int lane, int mask) { return __int_as_float(__builtin_amdgcn_ds_bpermute((lane ^ mask) << 2, __float_as_int(v))); }
; template <int DV, int MODE>
; DI void attn_item(const AttnArgs& a, char* smem) {
;     ...
;       mx = fmaxf(mx, shx(mx, lane, 32)) * SC;
;       const float mn = fmaxf(m, mx);
;       const bool resc = __builtin_amdgcn_ballot_w64(mn != m) != 0ull;
;       float ps0 = 0.f, ps1 = 0.f;
; #pragma unroll
;       for (int kb = 0; kb < 2; ++kb)
; #pragma unroll
;         for (int i = 0; i < 16; i += 2) {
;           f32x2n v = {s[kb][i], s[kb][i + 1]};
;           v = v * f32x2n{SC, SC} - f32x2n{mn, mn};
;           const float p0 = ex2(v.x), p1 = ex2(v.y);
;           s[kb][i] = p0; s[kb][i + 1] = p1;
;           ps0 += p0; ps1 += p1;
;         }
;       if (resc) {
;         const float alpha = ex2(m - mn);
;         m = mn;
.LBB0_542:
	v_mul_f32_e32 v34, 0x3e38aa3b, v141
	v_sub_f32_e32 v34, v34, v140
	v_cmp_lt_f32_e32 vcc, 8.0, v34
	s_cbranch_vccnz .Llz_7
	s_waitcnt lgkmcnt(0)
	v_mov_b32_e32 v34, v140
	s_branch .LBB0_544

; DI int crow(int i, int h) { return (i & 3) + 8 * (i >> 2) + 4 * h; }
; DI f32x16 mfma32(bf8 a, bf8 b, f32x16 c) { return __builtin_amdgcn_mfma_f32_32x32x16_bf16(a, b, c, 0, 0, 0); }
; DI float ex2(float x) { return __builtin_amdgcn_exp2f(x); }
; template <int DV, int MODE>
; DI void attn_item(const AttnArgs& a, char* smem) {
;     ...
;       f32x16 s[2];
; #pragma unroll
;       for (int kb = 0; kb < 2; ++kb) {
; #pragma unroll
;         for (int i = 0; i < 16; ++i) s[kb][i] = 0.f;
; #pragma unroll
;         for (int ks = 0; ks < 4; ++ks) {
;           const bf8 kf = *(const bf8*)(Ks + (kb * 32 + r) * 72 + ks * 16 + h * 8);
;           s[kb] = mfma32(kf, qf[ks], s[kb]);
;         }
;       }
;       constexpr float SC = 0.125f * LOG2E;
;       float mx = -INFINITY;
;       if (local) {
; #pragma unroll
;         for (int kb = 0; kb < 2; ++kb)
; #pragma unroll
;           for (int i = 0; i < 16; ++i) {
;             const int kc = kb * 32 + crow(i, h);
;             const bool ok = (kc >= cs) && (kc < cs + 16);
;             const int dc = kc - qc + 15;
;             const int dr = kr - rq + 7;
;             const float bias = rpbS[dr * 32 + (ok ? dc : 0)];
;             const float v = ok ? (s[kb][i] + bias * (1.f / SC)) : -INFINITY;
;             s[kb][i] = v;
;             mx = fmaxf(mx, v);
;           }
;       } else {
; #pragma unroll
;         for (int kb = 0; kb < 2; ++kb)
; #pragma unroll
;           for (int i = 0; i < 16; i += 2) mx = fmaxf(fmaxf(mx, s[kb][i]), s[kb][i + 1]);
;       }
;       mx = fmaxf(mx, shx(mx, lane, 32)) * SC;
;       const float mn = fmaxf(m, mx);
;       const bool resc = __builtin_amdgcn_ballot_w64(mn != m) != 0ull;
;       float ps0 = 0.f, ps1 = 0.f;
; #pragma unroll
;       for (int kb = 0; kb < 2; ++kb)
; #pragma unroll
;         for (int i = 0; i < 16; i += 2) {
;           f32x2n v = {s[kb][i], s[kb][i + 1]};
;           v = v * f32x2n{SC, SC} - f32x2n{mn, mn};
;           const float p0 = ex2(v.x), p1 = ex2(v.y);
;           s[kb][i] = p0; s[kb][i + 1] = p1;
;           ps0 += p0; ps1 += p1;
;         }
;       if (resc) {
;         const float alpha = ex2(m - mn);
;         m = mn;
;         lsum *= alpha;
; #pragma unroll
;         for (int d = 0; d < NDV; ++d)
; #pragma unroll
;           for (int i = 0; i < 16; ++i) O[d][i] *= alpha;
;       }
.LBB0_556:
	ds_read_b128 v[66:69], v153
	ds_read_b128 v[70:73], v153 offset:32
	ds_read_b128 v[156:159], v153 offset:4640
	s_waitcnt lgkmcnt(2)
	v_mfma_f32_32x32x16_bf16 v[82:97], v[66:69], v[98:101], 0
	ds_read_b128 v[66:69], v153 offset:64
	s_waitcnt lgkmcnt(2)
	v_mfma_f32_32x32x16_bf16 v[82:97], v[70:73], v[102:105], v[82:97]
	s_waitcnt lgkmcnt(0)
	v_mfma_f32_32x32x16_bf16 v[82:97], v[66:69], v[106:109], v[82:97]
	ds_read_b128 v[66:69], v153 offset:96
	s_waitcnt lgkmcnt(0)
	v_mfma_f32_32x32x16_bf16 v[82:97], v[66:69], v[110:113], v[82:97]
	ds_read_b128 v[66:69], v153 offset:4608
	s_waitcnt lgkmcnt(0)
	v_mfma_f32_32x32x16_bf16 v[66:81], v[66:69], v[98:101], 0
	s_nop 8
	v_max3_f32 v148, v82, s33, v83
	v_max3_f32 v148, v148, v84, v85
	v_max3_f32 v148, v148, v86, v87
	v_max3_f32 v148, v148, v88, v89
	v_max3_f32 v148, v148, v90, v91
	v_max3_f32 v148, v148, v92, v93
	v_max3_f32 v148, v148, v94, v95
	v_mfma_f32_32x32x16_bf16 v[66:81], v[156:159], v[102:105], v[66:81]
	ds_read_b128 v[156:159], v153 offset:4672
	v_max3_f32 v148, v148, v96, v97
	s_waitcnt lgkmcnt(0)
	v_mfma_f32_32x32x16_bf16 v[66:81], v[156:159], v[106:109], v[66:81]
	ds_read_b128 v[156:159], v153 offset:4704
	s_waitcnt lgkmcnt(0)
	v_mfma_f32_32x32x16_bf16 v[66:81], v[156:159], v[110:113], v[66:81]
	s_nop 11
	v_max3_f32 v148, v148, v66, v67
	v_max3_f32 v148, v148, v68, v69
	v_max3_f32 v148, v148, v70, v71
	v_max3_f32 v148, v148, v72, v73
	v_max3_f32 v148, v148, v74, v75
	v_max3_f32 v148, v148, v76, v77
	v_max3_f32 v148, v148, v78, v79
	v_max3_f32 v148, v148, v80, v81
	v_mul_f32_e32 v156, 0x3e38aa3b, v148
	v_sub_f32_e32 v156, v156, v155
	v_cmp_lt_f32_e32 vcc, 8.0, v156
	s_cbranch_vccnz .Llz_8
	v_mov_b32_e32 v148, v155
	s_branch .LBB0_553
.Llz_8:
	ds_bpermute_b32 v156, v137, v148
	s_waitcnt lgkmcnt(0)
	v_max_f32_e32 v156, v156, v156
	v_max_f32_e32 v148, v148, v156
	v_mul_f32_e32 v148, 0x3e38aa3b, v148
	v_max_f32_e32 v156, v155, v155
	v_max_f32_e32 v148, v156, v148
	v_cmp_neq_f32_e32 vcc, v148, v155
	s_cbranch_vccz .LBB0_553
	v_sub_f32_e32 v155, v155, v148
	v_exp_f32_e32 v156, v155
	v_mov_b32_e32 v155, v148
	v_pk_mul_f32 v[64:65], v[64:65], v[156:157] op_sel_hi:[1,0]
	v_pk_mul_f32 v[62:63], v[62:63], v[156:157] op_sel_hi:[1,0]
	v_pk_mul_f32 v[60:61], v[60:61], v[156:157] op_sel_hi:[1,0]
	v_pk_mul_f32 v[58:59], v[58:59], v[156:157] op_sel_hi:[1,0]
	v_pk_mul_f32 v[56:57], v[56:57], v[156:157] op_sel_hi:[1,0]
	v_pk_mul_f32 v[54:55], v[54:55], v[156:157] op_sel_hi:[1,0]
	v_pk_mul_f32 v[52:53], v[52:53], v[156:157] op_sel_hi:[1,0]
	v_pk_mul_f32 v[50:51], v[50:51], v[156:157] op_sel_hi:[1,0]
	v_pk_mul_f32 v[48:49], v[48:49], v[156:157] op_sel_hi:[1,0]
	v_pk_mul_f32 v[46:47], v[46:47], v[156:157] op_sel_hi:[1,0]
	v_pk_mul_f32 v[44:45], v[44:45], v[156:157] op_sel_hi:[1,0]
	v_pk_mul_f32 v[42:43], v[42:43], v[156:157] op_sel_hi:[1,0]
	v_pk_mul_f32 v[40:41], v[40:41], v[156:157] op_sel_hi:[1,0]
	v_pk_mul_f32 v[38:39], v[38:39], v[156:157] op_sel_hi:[1,0]
	v_pk_mul_f32 v[36:37], v[36:37], v[156:157] op_sel_hi:[1,0]
	v_pk_mul_f32 v[34:35], v[34:35], v[156:157] op_sel_hi:[1,0]
	v_pk_mul_f32 v[32:33], v[32:33], v[156:157] op_sel_hi:[1,0]
	v_pk_mul_f32 v[30:31], v[30:31], v[156:157] op_sel_hi:[1,0]
	v_pk_mul_f32 v[28:29], v[28:29], v[156:157] op_sel_hi:[1,0]
	v_pk_mul_f32 v[26:27], v[26:27], v[156:157] op_sel_hi:[1,0]
	v_pk_mul_f32 v[24:25], v[24:25], v[156:157] op_sel_hi:[1,0]
	v_pk_mul_f32 v[22:23], v[22:23], v[156:157] op_sel_hi:[1,0]
	v_pk_mul_f32 v[20:21], v[20:21], v[156:157] op_sel_hi:[1,0]
	v_pk_mul_f32 v[18:19], v[18:19], v[156:157] op_sel_hi:[1,0]
	v_pk_mul_f32 v[16:17], v[16:17], v[156:157] op_sel_hi:[1,0]
	v_pk_mul_f32 v[14:15], v[14:15], v[156:157] op_sel_hi:[1,0]
	v_pk_mul_f32 v[12:13], v[12:13], v[156:157] op_sel_hi:[1,0]
	v_pk_mul_f32 v[10:11], v[10:11], v[156:157] op_sel_hi:[1,0]
	v_pk_mul_f32 v[8:9], v[8:9], v[156:157] op_sel_hi:[1,0]
	v_pk_mul_f32 v[6:7], v[6:7], v[156:157] op_sel_hi:[1,0]
	v_pk_mul_f32 v[4:5], v[4:5], v[156:157] op_sel_hi:[1,0]
	v_pk_mul_f32 v[2:3], v[2:3], v[156:157] op_sel_hi:[1,0]
	v_mul_f32_e32 v152, v152, v156
	s_branch .LBB0_553
